# non-temporal hint on the f32 residual-stream stores of the fused epilogues
# speedup vs baseline: 1.0372x; 1.0140x over previous
;     __device__ __forceinline__ void fused(f32x4 (&acc)[2][2][4][2], const Unit& u, int wr, int wc, int fr, int fq, PG8_LAS unsigned char* lds, int wid, int lane) const {
;         const int row0 = u.pm * BM + wr * 64 + fr, col0 = u.pn * BM + wc * 32 + 4 * fq; const int bo = (u.pm >= 32 ? 9216 : 0); const float* gp = gate + bo + col0;
;         f32x4 gv[2][2];
; #pragma unroll
;         for (int bj = 0; bj < 2; ++bj)
; #pragma unroll
;             for (int n = 0; n < 2; ++n) gv[bj][n] = *(const f32x4*)(gp + bj * HALF + n * 16) * coef;
; #pragma unroll
;         for (int ai = 0; ai < 2; ++ai)
; #pragma unroll
;             for (int m = 0; m < 4; ++m) { const size_t off = (size_t)(row0 + ai * HALF + m * 16) * 1024 + col0;
; #pragma unroll
;                 for (int bj = 0; bj < 2; ++bj)
; #pragma unroll
;                     for (int n = 0; n < 2; ++n) { const f32x4 bs = *(const f32x4*)(base + off + bj * HALF + n * 16); acc[ai][bj][m][n] = bs + gv[bj][n] * acc[ai][bj][m][n]; *(f32x4*)(out + off + bj * HALF + n * 16) = acc[ai][bj][m][n]; }
.LBB0_387:
	v_readlane_b32 s0, v255, 17
	v_readlane_b32 s1, v255, 18
	s_and_b64 s[4:5], s[0:1], s[12:13]
	v_readlane_b32 s0, v255, 13
	s_or_b32 s0, s3, s0
	s_cmp_eq_u32 s0, 0
	v_readlane_b32 s0, v255, 21
	v_readlane_b32 s1, v255, 22
	s_cselect_b32 s7, s23, s21
	s_cselect_b32 s6, s22, s20
	s_lshl_b64 s[0:1], s[0:1], 2
	s_add_u32 s8, s14, s0
	s_addc_u32 s9, s15, s1
	s_and_b64 s[0:1], s[12:13], exec
	s_movk_i32 s0, 0x2000
	s_cselect_b32 s0, 0x8000, s0
	s_add_u32 s8, s8, s0
	s_addc_u32 s9, s9, 0
	s_lshl_b32 s1, s38, 5
	s_lshl_b32 s0, s37, 8
	s_lshl_b32 s23, s18, 8
	s_add_i32 s22, s0, s49
	s_or_b32 s1, s23, s1
	v_lshrrev_b32_e32 v0, 2, v153
	s_cmp_gt_i32 s37, 31
	v_and_or_b32 v140, v0, 12, s1
	s_cselect_b32 s1, 0x2400, 0
	s_lshl_b32 s1, s1, 2
	s_add_u32 s8, s8, s1
	s_addc_u32 s9, s9, 0
	v_ashrrev_i32_e32 v141, 31, v140
	v_lshl_add_u64 v[150:151], v[140:141], 2, s[8:9]
	s_barrier
	global_load_dwordx4 v[130:133], v[150:151], off
	global_load_dwordx4 v[154:157], v[150:151], off offset:576
	s_mov_b64 s[8:9], 0x80000
	s_and_b64 vcc, exec, s[4:5]
	s_movk_i32 s58, 0x7fff
	s_mov_b32 s59, 0xffff0000
	s_mov_b64 s[60:61], 0x1000
	s_waitcnt vmcnt(0)
	v_pk_mul_f32 v[144:145], v[132:133], 0.5 op_sel_hi:[1,0]
	v_pk_mul_f32 v[146:147], v[130:131], 0.5 op_sel_hi:[1,0]
	global_load_dwordx4 v[130:133], v[150:151], off offset:64
	s_waitcnt vmcnt(0)
	v_pk_mul_f32 v[138:139], v[132:133], 0.5 op_sel_hi:[1,0]
	v_pk_mul_f32 v[142:143], v[130:131], 0.5 op_sel_hi:[1,0]
	global_load_dwordx4 v[130:133], v[150:151], off offset:512
	v_or_b32_e32 v150, s22, v148
	v_ashrrev_i32_e32 v151, 31, v150
	v_lshlrev_b64 v[148:149], 10, v[150:151]
	v_lshl_add_u64 v[148:149], v[148:149], 0, v[140:141]
	v_lshlrev_b64 v[148:149], 2, v[148:149]
	v_lshl_add_u64 v[158:159], s[6:7], 0, v[148:149]
	v_lshl_add_u64 v[160:161], s[20:21], 0, v[148:149]
	s_waitcnt vmcnt(0)
	v_pk_mul_f32 v[134:135], v[132:133], 0.5 op_sel_hi:[1,0]
	v_pk_mul_f32 v[136:137], v[130:131], 0.5 op_sel_hi:[1,0]
	v_pk_mul_f32 v[130:131], v[156:157], 0.5 op_sel_hi:[1,0]
	v_pk_mul_f32 v[132:133], v[154:155], 0.5 op_sel_hi:[1,0]
	global_load_dwordx4 v[170:173], v[158:159], off nt
	global_load_dwordx4 v[174:177], v[158:159], off offset:64 nt
	global_load_dwordx4 v[178:181], v[158:159], off offset:512 nt
	global_load_dwordx4 v[182:185], v[158:159], off offset:576 nt
	s_waitcnt vmcnt(3)
	v_pk_fma_f32 v[116:117], v[116:117], v[144:145], v[172:173]
	v_pk_fma_f32 v[114:115], v[114:115], v[146:147], v[170:171]
	global_store_dwordx4 v[160:161], v[114:117], off nt
	s_waitcnt vmcnt(3)
	v_pk_fma_f32 v[84:85], v[84:85], v[138:139], v[176:177]
	v_pk_fma_f32 v[82:83], v[82:83], v[142:143], v[174:175]
	global_store_dwordx4 v[160:161], v[82:85], off offset:64 nt
	s_waitcnt vmcnt(3)
	v_pk_fma_f32 v[28:29], v[28:29], v[134:135], v[180:181]
	v_pk_fma_f32 v[26:27], v[26:27], v[136:137], v[178:179]
	global_store_dwordx4 v[160:161], v[26:29], off offset:512 nt
	s_waitcnt vmcnt(3)
	v_pk_fma_f32 v[2:3], v[2:3], v[132:133], v[182:183]
	v_or_b32_e32 v154, 16, v150
	v_ashrrev_i32_e32 v155, 31, v154
	v_lshlrev_b64 v[154:155], 10, v[154:155]
	v_lshl_add_u64 v[154:155], v[154:155], 0, v[140:141]
	v_pk_fma_f32 v[4:5], v[4:5], v[130:131], v[184:185]
	v_lshlrev_b64 v[158:159], 2, v[154:155]
	global_store_dwordx4 v[160:161], v[2:5], off offset:576 nt
	v_lshl_add_u64 v[160:161], s[6:7], 0, v[158:159]
	global_load_dwordx4 v[170:173], v[160:161], off nt
	global_load_dwordx4 v[174:177], v[160:161], off offset:64 nt
	global_load_dwordx4 v[178:181], v[160:161], off offset:512 nt
	global_load_dwordx4 v[182:185], v[160:161], off offset:576 nt
	v_lshl_add_u64 v[158:159], s[20:21], 0, v[158:159]
	s_waitcnt vmcnt(3)
	v_pk_fma_f32 v[124:125], v[124:125], v[144:145], v[172:173]
	v_pk_fma_f32 v[122:123], v[122:123], v[146:147], v[170:171]
	global_store_dwordx4 v[158:159], v[122:125], off nt
	s_waitcnt vmcnt(3)
	v_pk_fma_f32 v[96:97], v[96:97], v[138:139], v[176:177]
	v_pk_fma_f32 v[94:95], v[94:95], v[142:143], v[174:175]
	global_store_dwordx4 v[158:159], v[94:97], off offset:64 nt
	s_waitcnt vmcnt(3)
	v_pk_fma_f32 v[36:37], v[36:37], v[134:135], v[180:181]
	v_pk_fma_f32 v[34:35], v[34:35], v[136:137], v[178:179]
	global_store_dwordx4 v[158:159], v[34:37], off offset:512 nt
	s_waitcnt vmcnt(3)
	v_pk_fma_f32 v[6:7], v[6:7], v[132:133], v[182:183]
	v_or_b32_e32 v154, 32, v150
	v_ashrrev_i32_e32 v155, 31, v154
	v_lshlrev_b64 v[154:155], 10, v[154:155]
	v_pk_fma_f32 v[8:9], v[8:9], v[130:131], v[184:185]
	v_lshl_add_u64 v[154:155], v[154:155], 0, v[140:141]
	global_store_dwordx4 v[158:159], v[6:9], off offset:576 nt
	v_lshlrev_b64 v[158:159], 2, v[154:155]
	v_lshl_add_u64 v[160:161], s[6:7], 0, v[158:159]
	global_load_dwordx4 v[170:173], v[160:161], off nt
	global_load_dwordx4 v[174:177], v[160:161], off offset:64 nt
	global_load_dwordx4 v[178:181], v[160:161], off offset:512 nt
	global_load_dwordx4 v[182:185], v[160:161], off offset:576 nt
	v_lshl_add_u64 v[158:159], s[20:21], 0, v[158:159]
	v_or_b32_e32 v150, 48, v150
	v_ashrrev_i32_e32 v151, 31, v150
	v_lshlrev_b64 v[150:151], 10, v[150:151]
	v_lshl_add_u64 v[150:151], v[150:151], 0, v[140:141]
	v_lshlrev_b64 v[150:151], 2, v[150:151]
	s_waitcnt vmcnt(3)
	v_pk_fma_f32 v[128:129], v[128:129], v[144:145], v[172:173]
	v_pk_fma_f32 v[126:127], v[126:127], v[146:147], v[170:171]
	global_store_dwordx4 v[158:159], v[126:129], off nt
	s_waitcnt vmcnt(3)
	v_pk_fma_f32 v[108:109], v[108:109], v[138:139], v[176:177]
	v_pk_fma_f32 v[106:107], v[106:107], v[142:143], v[174:175]
	global_store_dwordx4 v[158:159], v[106:109], off offset:64 nt
	s_waitcnt vmcnt(3)
;     __device__ __forceinline__ void fused(f32x4 (&acc)[2][2][4][2], const Unit& u, int wr, int wc, int fr, int fq, PG8_LAS unsigned char* lds, int wid, int lane) const {
;     ...
;             for (int m = 0; m < 4; ++m) { const size_t off = (size_t)(row0 + ai * HALF + m * 16) * 1024 + col0;
; #pragma unroll
;                 for (int bj = 0; bj < 2; ++bj)
; #pragma unroll
;                     for (int n = 0; n < 2; ++n) { const f32x4 bs = *(const f32x4*)(base + off + bj * HALF + n * 16); acc[ai][bj][m][n] = bs + gv[bj][n] * acc[ai][bj][m][n]; *(f32x4*)(out + off + bj * HALF + n * 16) = acc[ai][bj][m][n]; }
;                 if (m & 1) asm volatile("" ::: "memory"); }
;         if (donorm == 0) return;
	v_pk_fma_f32 v[44:45], v[44:45], v[134:135], v[180:181]
	v_pk_fma_f32 v[42:43], v[42:43], v[136:137], v[178:179]
	global_store_dwordx4 v[158:159], v[42:45], off offset:512 nt
	s_waitcnt vmcnt(3)
	v_pk_fma_f32 v[12:13], v[12:13], v[130:131], v[184:185]
	v_pk_fma_f32 v[10:11], v[10:11], v[132:133], v[182:183]
	global_store_dwordx4 v[158:159], v[10:13], off offset:576 nt
	v_lshl_add_u64 v[158:159], s[6:7], 0, v[150:151]
	global_load_dwordx4 v[170:173], v[158:159], off nt
	global_load_dwordx4 v[174:177], v[158:159], off offset:64 nt
	global_load_dwordx4 v[178:181], v[158:159], off offset:512 nt
	global_load_dwordx4 v[182:185], v[158:159], off offset:576 nt
	v_lshl_add_u64 v[150:151], s[20:21], 0, v[150:151]
	s_waitcnt vmcnt(3)
	v_pk_fma_f32 v[120:121], v[120:121], v[144:145], v[172:173]
	v_pk_fma_f32 v[118:119], v[118:119], v[146:147], v[170:171]
	global_store_dwordx4 v[150:151], v[118:121], off nt
	s_waitcnt vmcnt(3)
	v_pk_fma_f32 v[112:113], v[112:113], v[138:139], v[176:177]
	v_pk_fma_f32 v[110:111], v[110:111], v[142:143], v[174:175]
	global_store_dwordx4 v[150:151], v[110:113], off offset:64 nt
	s_waitcnt vmcnt(3)
	v_pk_fma_f32 v[48:49], v[48:49], v[134:135], v[180:181]
	v_pk_fma_f32 v[46:47], v[46:47], v[136:137], v[178:179]
	global_store_dwordx4 v[150:151], v[46:49], off offset:512 nt
	s_waitcnt vmcnt(3)
	v_pk_fma_f32 v[16:17], v[16:17], v[130:131], v[184:185]
	v_pk_fma_f32 v[14:15], v[14:15], v[132:133], v[182:183]
	global_store_dwordx4 v[150:151], v[14:17], off offset:576 nt
	v_lshl_add_u64 v[150:151], v[148:149], 0, s[8:9]
	v_lshl_add_u64 v[158:159], s[6:7], 0, v[150:151]
	global_load_dwordx4 v[170:173], v[158:159], off nt
	global_load_dwordx4 v[174:177], v[158:159], off offset:64 nt
	global_load_dwordx4 v[178:181], v[158:159], off offset:512 nt
	global_load_dwordx4 v[182:185], v[158:159], off offset:576 nt
	v_lshl_add_u64 v[150:151], s[20:21], 0, v[150:151]
	s_mov_b64 s[8:9], 0x90000
	s_waitcnt vmcnt(3)
	v_pk_fma_f32 v[104:105], v[104:105], v[144:145], v[172:173]
	v_pk_fma_f32 v[102:103], v[102:103], v[146:147], v[170:171]
	global_store_dwordx4 v[150:151], v[102:105], off nt
	s_waitcnt vmcnt(3)
	v_pk_fma_f32 v[100:101], v[100:101], v[138:139], v[176:177]
	v_pk_fma_f32 v[98:99], v[98:99], v[142:143], v[174:175]
	global_store_dwordx4 v[150:151], v[98:101], off offset:64 nt
	s_waitcnt vmcnt(3)
	v_pk_fma_f32 v[56:57], v[56:57], v[134:135], v[180:181]
	v_pk_fma_f32 v[54:55], v[54:55], v[136:137], v[178:179]
	global_store_dwordx4 v[150:151], v[54:57], off offset:512 nt
	s_waitcnt vmcnt(3)
	v_pk_fma_f32 v[20:21], v[20:21], v[130:131], v[184:185]
	v_pk_fma_f32 v[18:19], v[18:19], v[132:133], v[182:183]
	global_store_dwordx4 v[150:151], v[18:21], off offset:576 nt
	v_lshl_add_u64 v[150:151], v[148:149], 0, s[8:9]
	v_lshl_add_u64 v[158:159], s[6:7], 0, v[150:151]
	global_load_dwordx4 v[170:173], v[158:159], off nt
	global_load_dwordx4 v[174:177], v[158:159], off offset:64 nt
	global_load_dwordx4 v[178:181], v[158:159], off offset:512 nt
	global_load_dwordx4 v[182:185], v[158:159], off offset:576 nt
	v_lshl_add_u64 v[150:151], s[20:21], 0, v[150:151]
	s_mov_b64 s[8:9], 0xa0000
	s_waitcnt vmcnt(3)
	v_pk_fma_f32 v[92:93], v[92:93], v[144:145], v[172:173]
	v_pk_fma_f32 v[90:91], v[90:91], v[146:147], v[170:171]
	global_store_dwordx4 v[150:151], v[90:93], off nt
	s_waitcnt vmcnt(3)
	v_pk_fma_f32 v[88:89], v[88:89], v[138:139], v[176:177]
	v_pk_fma_f32 v[86:87], v[86:87], v[142:143], v[174:175]
	global_store_dwordx4 v[150:151], v[86:89], off offset:64 nt
	s_waitcnt vmcnt(3)
	v_pk_fma_f32 v[60:61], v[60:61], v[134:135], v[180:181]
	v_pk_fma_f32 v[58:59], v[58:59], v[136:137], v[178:179]
	global_store_dwordx4 v[150:151], v[58:61], off offset:512 nt
	s_waitcnt vmcnt(3)
	v_pk_fma_f32 v[32:33], v[32:33], v[130:131], v[184:185]
	v_pk_fma_f32 v[30:31], v[30:31], v[132:133], v[182:183]
	global_store_dwordx4 v[150:151], v[30:33], off offset:576 nt
	v_lshl_add_u64 v[150:151], v[148:149], 0, s[8:9]
	v_lshl_add_u64 v[158:159], s[6:7], 0, v[150:151]
	global_load_dwordx4 v[170:173], v[158:159], off nt
	global_load_dwordx4 v[174:177], v[158:159], off offset:64 nt
	global_load_dwordx4 v[178:181], v[158:159], off offset:512 nt
	global_load_dwordx4 v[182:185], v[158:159], off offset:576 nt
	v_lshl_add_u64 v[150:151], s[20:21], 0, v[150:151]
	s_mov_b64 s[8:9], 0xb0000
	s_waitcnt vmcnt(3)
	v_pk_fma_f32 v[80:81], v[80:81], v[144:145], v[172:173]
	v_pk_fma_f32 v[78:79], v[78:79], v[146:147], v[170:171]
	global_store_dwordx4 v[150:151], v[78:81], off nt
	s_waitcnt vmcnt(3)
	v_pk_fma_f32 v[76:77], v[76:77], v[138:139], v[176:177]
	v_pk_fma_f32 v[74:75], v[74:75], v[142:143], v[174:175]
	global_store_dwordx4 v[150:151], v[74:77], off offset:64 nt
	s_waitcnt vmcnt(3)
	v_pk_fma_f32 v[64:65], v[64:65], v[134:135], v[180:181]
	v_pk_fma_f32 v[62:63], v[62:63], v[136:137], v[178:179]
	global_store_dwordx4 v[150:151], v[62:65], off offset:512 nt
	s_waitcnt vmcnt(3)
	v_pk_fma_f32 v[40:41], v[40:41], v[130:131], v[184:185]
	v_pk_fma_f32 v[38:39], v[38:39], v[132:133], v[182:183]
	v_lshl_add_u64 v[154:155], v[148:149], 0, s[8:9]
	global_store_dwordx4 v[150:151], v[38:41], off offset:576 nt
	v_lshl_add_u64 v[156:157], s[6:7], 0, v[154:155]
	global_load_dwordx4 v[170:173], v[156:157], off nt
	global_load_dwordx4 v[174:177], v[156:157], off offset:64 nt
	global_load_dwordx4 v[178:181], v[156:157], off offset:512 nt
	global_load_dwordx4 v[182:185], v[156:157], off offset:576 nt
	s_waitcnt vmcnt(3)
	v_pk_fma_f32 v[72:73], v[72:73], v[144:145], v[172:173]
	v_pk_fma_f32 v[70:71], v[70:71], v[146:147], v[170:171]
	v_lshl_add_u64 v[148:149], s[20:21], 0, v[154:155]
	global_store_dwordx4 v[148:149], v[70:73], off nt
	s_waitcnt vmcnt(3)
	v_pk_fma_f32 v[68:69], v[68:69], v[138:139], v[176:177]
	v_pk_fma_f32 v[66:67], v[66:67], v[142:143], v[174:175]
	global_store_dwordx4 v[148:149], v[66:69], off offset:64 nt
	s_waitcnt vmcnt(3)
	v_pk_fma_f32 v[52:53], v[52:53], v[134:135], v[180:181]
	v_pk_fma_f32 v[50:51], v[50:51], v[136:137], v[178:179]
	global_store_dwordx4 v[148:149], v[50:53], off offset:512 nt
	s_waitcnt vmcnt(3)
	v_pk_fma_f32 v[24:25], v[24:25], v[130:131], v[184:185]
	v_pk_fma_f32 v[22:23], v[22:23], v[132:133], v[182:183]
	global_store_dwordx4 v[148:149], v[22:25], off offset:576 nt
	s_cbranch_vccnz .LBB0_425
;     __device__ __forceinline__ void fused(f32x4 (&acc)[2][2][4][2], const Unit& u, int wr, int wc, int fr, int fq, PG8_LAS unsigned char* lds, int wid, int lane) const {
;     ...
;             for (int m = 0; m < 4; ++m) { float q = 0.f;
; #pragma unroll
;                 for (int bj = 0; bj < 2; ++bj)
; #pragma unroll
;                     for (int n = 0; n < 2; ++n) { const f32x4 x = acc[ai][bj][m][n]; q += (x[0] * x[0] + x[1] * x[1]) + (x[2] * x[2] + x[3] * x[3]); }
;                 q += __shfl_xor(q, 16); q += __shfl_xor(q, 32);
;                 if (fq == 0) P[(ai * HALF + wr * 64 + m * 16 + fr) * 4 + wc] = q; }
	v_mul_f32_e32 v132, v115, v115
	v_mul_f32_e32 v133, v117, v117
	v_fmac_f32_e32 v132, v114, v114
	v_fmac_f32_e32 v133, v116, v116
	v_add_f32_e32 v132, v132, v133
	v_mul_f32_e32 v133, v83, v83
	v_mul_f32_e32 v134, v85, v85
	v_fmac_f32_e32 v133, v82, v82
	v_fmac_f32_e32 v134, v84, v84
	v_add_f32_e32 v133, v133, v134
	v_add_f32_e32 v132, v132, v133
	v_mul_f32_e32 v133, v27, v27
	v_mul_f32_e32 v134, v29, v29
	v_fmac_f32_e32 v133, v26, v26
	v_fmac_f32_e32 v134, v28, v28
	v_and_b32_e32 v131, 64, v240
	v_add_f32_e32 v133, v133, v134
	v_xor_b32_e32 v130, 16, v240
	v_add_u32_e32 v131, 64, v131
	v_add_f32_e32 v132, v132, v133
	v_mul_f32_e32 v133, v3, v3
	v_mul_f32_e32 v134, v5, v5
	v_cmp_lt_i32_e32 vcc, v130, v131
	v_fmac_f32_e32 v133, v2, v2
	v_fmac_f32_e32 v134, v4, v4
	v_cndmask_b32_e32 v130, v240, v130, vcc
	v_add_f32_e32 v133, v133, v134
	v_lshlrev_b32_e32 v130, 2, v130
	v_add_f32_e32 v133, v132, v133
	ds_bpermute_b32 v134, v130, v133
	v_xor_b32_e32 v132, 32, v240
	v_cmp_lt_i32_e32 vcc, v132, v131
	s_lshl_b32 s4, s38, 2
	v_and_b32_e32 v0, 63, v153
	v_cndmask_b32_e32 v131, v240, v132, vcc
	v_lshlrev_b32_e32 v132, 2, v131
	s_waitcnt lgkmcnt(0)
	v_add_f32_e32 v133, v133, v134
	ds_bpermute_b32 v134, v132, v133
	s_add_i32 s4, s4, 0
	v_cmp_gt_u32_e32 vcc, 16, v0
	v_lshl_add_u32 v131, v152, 4, s4
	s_and_saveexec_b64 s[4:5], vcc
	s_cbranch_execz .LBB0_390
	s_waitcnt lgkmcnt(0)
	v_add_f32_e32 v133, v133, v134
	ds_write_b32 v131, v133

;     __device__ __forceinline__ void fused(f32x4 (&acc)[2][2][4][2], const Unit& u, int wr, int wc, int fr, int fq, PG8_LAS unsigned char* lds, int wid, int lane) const {
;         const int row0 = u.pm * BM + wr * 64 + fr, col0 = u.pn * BM + wc * 32 + 4 * fq; const int bo = (u.pm >= 32 ? 9216 : 0); const float* gp = gate + bo + col0;
;         f32x4 gv[2][2];
; #pragma unroll
;         for (int bj = 0; bj < 2; ++bj)
; #pragma unroll
;             for (int n = 0; n < 2; ++n) gv[bj][n] = *(const f32x4*)(gp + bj * HALF + n * 16) * coef;
; #pragma unroll
;         for (int ai = 0; ai < 2; ++ai)
; #pragma unroll
;             for (int m = 0; m < 4; ++m) { const size_t off = (size_t)(row0 + ai * HALF + m * 16) * 1024 + col0;
; #pragma unroll
;                 for (int bj = 0; bj < 2; ++bj)
; #pragma unroll
;                     for (int n = 0; n < 2; ++n) { const f32x4 bs = *(const f32x4*)(base + off + bj * HALF + n * 16); acc[ai][bj][m][n] = bs + gv[bj][n] * acc[ai][bj][m][n]; *(f32x4*)(out + off + bj * HALF + n * 16) = acc[ai][bj][m][n]; }
.LBB0_1157:
	v_readlane_b32 s0, v255, 21
	v_readlane_b32 s1, v255, 22
	s_lshl_b64 s[4:5], s[0:1], 2
	s_add_u32 s1, s8, s4
	s_addc_u32 s18, s9, s5
	s_lshl_b32 s0, s12, 8
	s_lshl_b32 s4, s13, 5
	s_add_i32 s6, s0, s45
	s_lshl_b32 s5, s14, 8
	s_or_b32 s4, s5, s4
	v_lshrrev_b32_e32 v0, 2, v173
	v_or_b32_e32 v186, s6, v142
	v_and_or_b32 v162, v0, 12, s4
	s_cmp_gt_i32 s12, 31
	v_ashrrev_i32_e32 v187, 31, v186
	s_cselect_b32 s4, 0x2400, 0
	v_ashrrev_i32_e32 v163, 31, v162
	v_lshlrev_b64 v[142:143], 12, v[186:187]
	s_lshl_b32 s19, s4, 2
	v_lshlrev_b64 v[164:165], 2, v[162:163]
	v_lshl_add_u64 v[142:143], s[16:17], 0, v[142:143]
	s_add_u32 s4, s1, s19
	v_lshl_add_u64 v[166:167], v[142:143], 0, v[164:165]
	v_or_b32_e32 v142, 16, v186
	s_addc_u32 s5, s18, 0
	v_ashrrev_i32_e32 v143, 31, v142
	v_lshl_add_u64 v[144:145], s[4:5], 0, v[164:165]
	s_mov_b64 s[4:5], 0x5000
	v_lshlrev_b64 v[142:143], 12, v[142:143]
	v_lshl_add_u64 v[134:135], v[144:145], 0, s[4:5]
	v_lshl_add_u64 v[142:143], s[16:17], 0, v[142:143]
	s_movk_i32 s4, 0x5000
	v_lshl_add_u64 v[188:189], v[142:143], 0, v[164:165]
	v_add_co_u32_e32 v142, vcc, s4, v144
	s_barrier
	s_nop 0
	v_addc_co_u32_e32 v143, vcc, 0, v145, vcc
	global_load_dwordx4 v[138:141], v[134:135], off offset:64
	global_load_dwordx4 v[130:133], v[134:135], off offset:512
	s_nop 0
	global_load_dwordx4 v[134:137], v[134:135], off offset:576
	s_nop 0
	global_load_dwordx4 v[146:149], v[166:167], off offset:64
	global_load_dwordx4 v[150:153], v[166:167], off offset:512
	global_load_dwordx4 v[154:157], v[166:167], off offset:576
	global_load_dwordx4 v[158:161], v[188:189], off offset:64
	global_load_dwordx4 v[168:171], v[188:189], off offset:512
	global_load_dwordx4 v[174:177], v[188:189], off offset:576
	s_nop 0
	global_load_dwordx4 v[142:145], v[142:143], off
	s_nop 0
	global_load_dwordx4 v[178:181], v[166:167], off
	global_load_dwordx4 v[182:185], v[188:189], off
	v_or_b32_e32 v190, 32, v186
	v_or_b32_e32 v186, 48, v186
	v_ashrrev_i32_e32 v191, 31, v190
	v_lshlrev_b64 v[190:191], 12, v[190:191]
	v_ashrrev_i32_e32 v187, 31, v186
	v_lshl_add_u64 v[190:191], s[16:17], 0, v[190:191]
	v_lshl_add_u64 v[190:191], v[190:191], 0, v[164:165]
	s_mov_b64 s[4:5], 0x80000
	v_and_b32_e32 v0, 63, v173
	s_waitcnt vmcnt(0)
	v_pk_fma_f32 v[88:89], v[88:89], v[140:141], v[148:149]
	v_pk_fma_f32 v[86:87], v[86:87], v[138:139], v[146:147]
	v_pk_fma_f32 v[24:25], v[24:25], v[132:133], v[152:153]
	v_pk_fma_f32 v[22:23], v[22:23], v[130:131], v[150:151]
	v_pk_fma_f32 v[8:9], v[8:9], v[136:137], v[156:157]
	v_pk_fma_f32 v[6:7], v[6:7], v[134:135], v[154:155]
	v_pk_fma_f32 v[84:85], v[84:85], v[140:141], v[160:161]
	v_pk_fma_f32 v[82:83], v[82:83], v[138:139], v[158:159]
	v_pk_fma_f32 v[20:21], v[20:21], v[132:133], v[170:171]
	v_pk_fma_f32 v[18:19], v[18:19], v[130:131], v[168:169]
	v_pk_fma_f32 v[4:5], v[4:5], v[136:137], v[176:177]
	v_pk_fma_f32 v[2:3], v[2:3], v[134:135], v[174:175]
	v_pk_fma_f32 v[128:129], v[128:129], v[144:145], v[180:181]
	v_pk_fma_f32 v[126:127], v[126:127], v[142:143], v[178:179]
	v_pk_fma_f32 v[116:117], v[116:117], v[144:145], v[184:185]
	v_pk_fma_f32 v[114:115], v[114:115], v[142:143], v[182:183]
	global_store_dwordx4 v[166:167], v[86:89], off offset:64 nt
	global_store_dwordx4 v[166:167], v[22:25], off offset:512 nt
	global_store_dwordx4 v[166:167], v[6:9], off offset:576 nt
	global_store_dwordx4 v[188:189], v[82:85], off offset:64 nt
	global_store_dwordx4 v[188:189], v[18:21], off offset:512 nt
	global_store_dwordx4 v[188:189], v[2:5], off offset:576 nt
	global_store_dwordx4 v[166:167], v[126:129], off nt
	global_store_dwordx4 v[188:189], v[114:117], off nt
	v_lshlrev_b64 v[146:147], 12, v[186:187]
	v_lshl_add_u64 v[146:147], s[16:17], 0, v[146:147]
	global_load_dwordx4 v[150:153], v[190:191], off nt
	global_load_dwordx4 v[154:157], v[190:191], off offset:64 nt
	v_lshl_add_u64 v[192:193], v[146:147], 0, v[164:165]
	global_load_dwordx4 v[158:161], v[190:191], off offset:512 nt
	global_load_dwordx4 v[168:171], v[190:191], off offset:576 nt
	global_load_dwordx4 v[174:177], v[192:193], off nt
	global_load_dwordx4 v[178:181], v[192:193], off offset:64 nt
	global_load_dwordx4 v[182:185], v[192:193], off offset:512 nt
	global_load_dwordx4 v[186:189], v[192:193], off offset:576 nt
	v_lshl_add_u64 v[146:147], v[166:167], 0, s[4:5]
	s_mov_b32 s4, 0x80000
	v_add_co_u32_e32 v148, vcc, s4, v166
	s_mov_b32 s4, 0x90000
	s_nop 0
	v_addc_co_u32_e32 v149, vcc, 0, v167, vcc
	v_add_co_u32_e32 v194, vcc, s4, v166
	s_mov_b64 s[4:5], 0x90000
	s_nop 0
	v_addc_co_u32_e32 v195, vcc, 0, v167, vcc
	v_lshl_add_u64 v[196:197], v[166:167], 0, s[4:5]
	s_mov_b64 s[4:5], 0xa0000
	v_mul_f32_e32 v200, v127, v127
	v_mul_f32_e32 v201, v129, v129
	v_fmac_f32_e32 v200, v126, v126
	v_fmac_f32_e32 v201, v128, v128
	v_mul_f32_e32 v198, v7, v7
	v_mul_f32_e32 v199, v9, v9
	v_fmac_f32_e32 v198, v6, v6
	v_fmac_f32_e32 v199, v8, v8
	s_waitcnt vmcnt(7)
	v_pk_fma_f32 v[124:125], v[124:125], v[144:145], v[152:153]
	v_pk_fma_f32 v[122:123], v[122:123], v[142:143], v[150:151]
	s_waitcnt vmcnt(6)
	v_pk_fma_f32 v[108:109], v[108:109], v[140:141], v[156:157]
	v_pk_fma_f32 v[106:107], v[106:107], v[138:139], v[154:155]
	s_waitcnt vmcnt(5)
	v_pk_fma_f32 v[40:41], v[40:41], v[132:133], v[160:161]
	v_pk_fma_f32 v[38:39], v[38:39], v[130:131], v[158:159]
	s_waitcnt vmcnt(4)
	v_pk_fma_f32 v[12:13], v[12:13], v[136:137], v[170:171]
	v_pk_fma_f32 v[10:11], v[10:11], v[134:135], v[168:169]
	s_waitcnt vmcnt(3)
	v_pk_fma_f32 v[120:121], v[120:121], v[144:145], v[176:177]
	v_pk_fma_f32 v[118:119], v[118:119], v[142:143], v[174:175]
	s_waitcnt vmcnt(2)
;     __device__ __forceinline__ void fused(f32x4 (&acc)[2][2][4][2], const Unit& u, int wr, int wc, int fr, int fq, PG8_LAS unsigned char* lds, int wid, int lane) const {
;     ...
;             for (int m = 0; m < 4; ++m) { const size_t off = (size_t)(row0 + ai * HALF + m * 16) * 1024 + col0;
; #pragma unroll
;                 for (int bj = 0; bj < 2; ++bj)
; #pragma unroll
;                     for (int n = 0; n < 2; ++n) { const f32x4 bs = *(const f32x4*)(base + off + bj * HALF + n * 16); acc[ai][bj][m][n] = bs + gv[bj][n] * acc[ai][bj][m][n]; *(f32x4*)(out + off + bj * HALF + n * 16) = acc[ai][bj][m][n]; }
;     ...
;             for (int m = 0; m < 4; ++m) { float q = 0.f;
; #pragma unroll
;                 for (int bj = 0; bj < 2; ++bj)
; #pragma unroll
;                     for (int n = 0; n < 2; ++n) { const f32x4 x = acc[ai][bj][m][n]; q += (x[0] * x[0] + x[1] * x[1]) + (x[2] * x[2] + x[3] * x[3]); }
;                 q += __shfl_xor(q, 16); q += __shfl_xor(q, 32);
	v_pk_fma_f32 v[112:113], v[112:113], v[140:141], v[180:181]
	v_pk_fma_f32 v[110:111], v[110:111], v[138:139], v[178:179]
	s_waitcnt vmcnt(1)
	v_pk_fma_f32 v[36:37], v[36:37], v[132:133], v[184:185]
	v_pk_fma_f32 v[34:35], v[34:35], v[130:131], v[182:183]
	s_waitcnt vmcnt(0)
	v_pk_fma_f32 v[16:17], v[16:17], v[136:137], v[188:189]
	v_pk_fma_f32 v[14:15], v[14:15], v[134:135], v[186:187]
	global_store_dwordx4 v[190:191], v[122:125], off nt
	global_store_dwordx4 v[190:191], v[106:109], off offset:64 nt
	global_store_dwordx4 v[190:191], v[38:41], off offset:512 nt
	global_store_dwordx4 v[190:191], v[10:13], off offset:576 nt
	global_store_dwordx4 v[192:193], v[118:121], off nt
	global_store_dwordx4 v[192:193], v[110:113], off offset:64 nt
	global_store_dwordx4 v[192:193], v[34:37], off offset:512 nt
	global_store_dwordx4 v[192:193], v[14:17], off offset:576 nt
	global_load_dwordx4 v[150:153], v[148:149], off nt
	global_load_dwordx4 v[154:157], v[146:147], off offset:64 nt
	global_load_dwordx4 v[158:161], v[146:147], off offset:512 nt
	global_load_dwordx4 v[174:177], v[146:147], off offset:576 nt
	global_load_dwordx4 v[178:181], v[194:195], off nt
	global_load_dwordx4 v[182:185], v[196:197], off offset:64 nt
	global_load_dwordx4 v[186:189], v[196:197], off offset:512 nt
	global_load_dwordx4 v[190:193], v[196:197], off offset:576 nt
	v_lshl_add_u64 v[168:169], v[166:167], 0, s[4:5]
	s_mov_b32 s4, 0xa0000
	v_add_co_u32_e32 v170, vcc, s4, v166
	s_mov_b32 s4, 0xb0000
	s_nop 0
	v_addc_co_u32_e32 v171, vcc, 0, v167, vcc
	s_waitcnt vmcnt(7)
	v_pk_fma_f32 v[104:105], v[104:105], v[144:145], v[152:153]
	v_pk_fma_f32 v[102:103], v[102:103], v[142:143], v[150:151]
	s_waitcnt vmcnt(6)
	v_pk_fma_f32 v[100:101], v[100:101], v[140:141], v[156:157]
	v_pk_fma_f32 v[98:99], v[98:99], v[138:139], v[154:155]
	s_waitcnt vmcnt(5)
	v_pk_fma_f32 v[52:53], v[52:53], v[132:133], v[160:161]
	v_pk_fma_f32 v[50:51], v[50:51], v[130:131], v[158:159]
	s_waitcnt vmcnt(4)
	v_pk_fma_f32 v[28:29], v[28:29], v[136:137], v[176:177]
	v_pk_fma_f32 v[26:27], v[26:27], v[134:135], v[174:175]
	s_waitcnt vmcnt(3)
	v_pk_fma_f32 v[96:97], v[96:97], v[144:145], v[180:181]
	v_pk_fma_f32 v[94:95], v[94:95], v[142:143], v[178:179]
	s_waitcnt vmcnt(2)
	v_pk_fma_f32 v[92:93], v[92:93], v[140:141], v[184:185]
	v_pk_fma_f32 v[90:91], v[90:91], v[138:139], v[182:183]
	s_waitcnt vmcnt(1)
	v_pk_fma_f32 v[48:49], v[48:49], v[132:133], v[188:189]
	v_pk_fma_f32 v[46:47], v[46:47], v[130:131], v[186:187]
	s_waitcnt vmcnt(0)
	v_pk_fma_f32 v[32:33], v[32:33], v[136:137], v[192:193]
	v_pk_fma_f32 v[30:31], v[30:31], v[134:135], v[190:191]
	global_store_dwordx4 v[148:149], v[102:105], off nt
	global_store_dwordx4 v[146:147], v[98:101], off offset:64 nt
	global_store_dwordx4 v[146:147], v[50:53], off offset:512 nt
	global_store_dwordx4 v[146:147], v[26:29], off offset:576 nt
	global_store_dwordx4 v[194:195], v[94:97], off nt
	global_store_dwordx4 v[196:197], v[90:93], off offset:64 nt
	global_store_dwordx4 v[196:197], v[46:49], off offset:512 nt
	global_store_dwordx4 v[196:197], v[30:33], off offset:576 nt
	v_add_co_u32_e32 v192, vcc, s4, v166
	s_mov_b64 s[4:5], 0xb0000
	s_nop 0
	v_addc_co_u32_e32 v193, vcc, 0, v167, vcc
	v_lshl_add_u64 v[194:195], v[166:167], 0, s[4:5]
	global_load_dwordx4 v[158:161], v[170:171], off nt
	global_load_dwordx4 v[154:157], v[168:169], off offset:64 nt
	global_load_dwordx4 v[150:153], v[168:169], off offset:512 nt
	global_load_dwordx4 v[146:149], v[168:169], off offset:576 nt
	global_load_dwordx4 v[176:179], v[192:193], off nt
	global_load_dwordx4 v[180:183], v[194:195], off offset:64 nt
	global_load_dwordx4 v[184:187], v[194:195], off offset:512 nt
	global_load_dwordx4 v[188:191], v[194:195], off offset:576 nt
	v_mul_f32_e32 v174, v87, v87
	v_mul_f32_e32 v175, v89, v89
	v_mul_f32_e32 v196, v23, v23
	v_mul_f32_e32 v197, v25, v25
	v_and_b32_e32 v167, 64, v240
	v_fmac_f32_e32 v174, v86, v86
	v_fmac_f32_e32 v175, v88, v88
	v_fmac_f32_e32 v196, v22, v22
	v_fmac_f32_e32 v197, v24, v24
	v_xor_b32_e32 v166, 16, v240
	v_add_u32_e32 v167, 64, v167
	v_add_f32_e32 v174, v174, v175
	v_add_f32_e32 v175, v196, v197
	v_add_f32_e32 v197, v200, v201
	v_cmp_lt_i32_e32 vcc, v166, v167
	v_add_f32_e32 v174, v197, v174
	v_add_f32_e32 v196, v198, v199
	v_cndmask_b32_e32 v166, v240, v166, vcc
	v_add_f32_e32 v174, v174, v175
	v_lshlrev_b32_e32 v166, 2, v166
	v_add_f32_e32 v174, v174, v196
	ds_bpermute_b32 v175, v166, v174
	v_xor_b32_e32 v196, 32, v240
	v_cmp_lt_i32_e32 vcc, v196, v167
	s_lshl_b32 s4, s13, 2
	s_add_i32 s4, s4, 0
	v_cndmask_b32_e32 v167, v240, v196, vcc
	v_lshlrev_b32_e32 v167, 2, v167
	s_waitcnt lgkmcnt(0)
	v_add_f32_e32 v174, v174, v175
	ds_bpermute_b32 v175, v167, v174
	v_cmp_gt_u32_e32 vcc, 16, v0
	s_waitcnt vmcnt(7)
	v_pk_fma_f32 v[80:81], v[80:81], v[144:145], v[160:161]
	v_pk_fma_f32 v[78:79], v[78:79], v[142:143], v[158:159]
	s_waitcnt vmcnt(6)
	v_pk_fma_f32 v[76:77], v[76:77], v[140:141], v[156:157]
	v_pk_fma_f32 v[74:75], v[74:75], v[138:139], v[154:155]
	s_waitcnt vmcnt(5)
	v_pk_fma_f32 v[64:65], v[64:65], v[132:133], v[152:153]
	v_pk_fma_f32 v[62:63], v[62:63], v[130:131], v[150:151]
	s_waitcnt vmcnt(4)
	v_pk_fma_f32 v[56:57], v[56:57], v[136:137], v[148:149]
	v_pk_fma_f32 v[54:55], v[54:55], v[134:135], v[146:147]
	s_waitcnt vmcnt(3)
	v_pk_fma_f32 v[72:73], v[72:73], v[144:145], v[178:179]
	v_pk_fma_f32 v[70:71], v[70:71], v[142:143], v[176:177]
	s_waitcnt vmcnt(2)
	v_pk_fma_f32 v[68:69], v[68:69], v[140:141], v[182:183]
	v_pk_fma_f32 v[66:67], v[66:67], v[138:139], v[180:181]
	s_waitcnt vmcnt(1)
	v_pk_fma_f32 v[60:61], v[60:61], v[132:133], v[186:187]
	v_pk_fma_f32 v[58:59], v[58:59], v[130:131], v[184:185]
	s_waitcnt vmcnt(0)
	v_pk_fma_f32 v[44:45], v[44:45], v[136:137], v[190:191]
	v_pk_fma_f32 v[42:43], v[42:43], v[134:135], v[188:189]
	global_store_dwordx4 v[170:171], v[78:81], off nt
	global_store_dwordx4 v[168:169], v[74:77], off offset:64 nt
	global_store_dwordx4 v[168:169], v[62:65], off offset:512 nt
	global_store_dwordx4 v[168:169], v[54:57], off offset:576 nt
	global_store_dwordx4 v[192:193], v[70:73], off nt
	global_store_dwordx4 v[194:195], v[66:69], off offset:64 nt
	global_store_dwordx4 v[194:195], v[58:61], off offset:512 nt
	global_store_dwordx4 v[194:195], v[42:45], off offset:576 nt
	v_lshl_add_u32 v130, v172, 4, s4
	s_and_saveexec_b64 s[4:5], vcc
	s_cbranch_execz .LBB0_1159
	s_waitcnt lgkmcnt(0)
	v_add_f32_e32 v131, v174, v175
	ds_write_b32 v130, v131
